# attention: skip chunks whose keys are all >= L (exact zero contribution); conv U staging halos via DPP wave_shr/wave_shl with only edge lanes loading
# speedup vs baseline: 1.0036x; 1.0008x over previous
; #define LAS __attribute__((address_space(3)))
; __device__ __forceinline__ bf16x8 attn_scores(const f32x4 s0, const f32x4 s1, const LAS float* bt, int cs, bool interior, bool metal, int g, int qpos, int L, float& den) {
;     ...
; #pragma unroll
;         for (int e = 0; e < 8; ++e) {
;             const float sv = e < 4 ? s0[e & 3] : s1[e & 3];
;             const int relb = cs + e, pos = relb + qpos;
;             const int relm = 8 * g + e - qpos;
;             const bool bvalid = ((unsigned)(relb + 128) <= 256u) && ((unsigned)(pos - 16) < (unsigned)(L - 16));
;             const int rel = metal ? relm : relb;
;             const bool valid = metal || bvalid;
;             const int relc = rel < -128 ? -128 : (rel > 128 ? 128 : rel);
; __device__ __forceinline__ void attn_phase(LAS unsigned char* lds, const Args& a, int j, int bid, int G, int tid) {
;     ...
;                 for (int i = 0; i < 10; ++i) {
;                     const int chunk = i == 0 ? 0 : cb + i - 1;
;                     const int kb = lkoff + 32 * chunk * KSTR;
;                     const bf16x8 k00 = *(const LAS bf16x8*)(lds + kb), k01 = *(const LAS bf16x8*)(lds + kb + 64);
;                     const bf16x8 k10 = *(const LAS bf16x8*)(lds + kb + 4 * KSTR), k11 = *(const LAS bf16x8*)(lds + kb + 4 * KSTR + 64);
;                     const f32x4 z4 = (f32x4){0.f, 0.f, 0.f, 0.f};
;                     f32x4 s0[4], s1[4];
; #pragma unroll
;                     for (int h = 0; h < 4; ++h) { s0[h] = __builtin_amdgcn_mfma_f32_16x16x32_bf16(k00, qf0[h], z4, 0, 0, 0); s1[h] = __builtin_amdgcn_mfma_f32_16x16x32_bf16(k10, qf0[h], z4, 0, 0, 0); }
; #pragma unroll
;                     for (int h = 0; h < 4; ++h) { s0[h] = __builtin_amdgcn_mfma_f32_16x16x32_bf16(k01, qf1[h], s0[h], 0, 0, 0); s1[h] = __builtin_amdgcn_mfma_f32_16x16x32_bf16(k11, qf1[h], s1[h], 0, 0, 0); }
;                     const int cs = start - 16 - q0 + 32 * chunk + lb;
;                     const int pmin = start + 32 * chunk - 16;
;                     const bool interior = (chunk > 0) && (pmin >= q0 + 15 - 128) && (pmin + 31 <= q0 + 128) && (pmin >= 16) && (pmin + 31 < L);
;                     const bool metal = (chunk == 0) && (g < 2);
;                     bf16x8 pa[4];
; #pragma unroll
;                     for (int h = 0; h < 4; ++h) pa[h] = attn_scores(s0[h], s1[h], bt[h], cs, interior, metal, g, qpos, L, den[h]);
.LBB0_713:
	s_add_i32 s6, s46, s39
	s_cmp_lg_u32 s39, 0
	s_cselect_b32 s42, s6, 0
	s_mul_i32 s6, s42, 0x1200
	v_add_u32_e32 v16, s6, v173
	s_lshl_b32 s6, s42, 5
	s_add_i32 s24, s58, s6
	s_add_i32 s22, s47, 16
	s_cmp_ge_i32 s24, s22
	s_cbranch_scc1 .Lattn_skipchunk
	s_cmp_gt_i32 s42, 0
	v_add_u32_e32 v237, s6, v200
	s_cselect_b64 s[6:7], -1, 0
	s_cmp_ge_i32 s24, s28
	ds_read_b128 v[0:3], v16
	ds_read_b128 v[4:7], v16 offset:64
	ds_read_b128 v[12:15], v16 offset:576
	ds_read_b128 v[134:137], v16 offset:640
	v_lshl_add_u32 v214, s42, 6, v175
	ds_read_b128 v[148:151], v214 offset:59904
	v_add_u32_e32 v214, 0xea00, v214
	ds_read_b128 v[154:157], v214 offset:13568
	ds_read_b128 v[204:207], v214 offset:27136
	ds_read_b128 v[208:211], v214 offset:40704
	v_lshl_add_u32 v214, v237, 2, s63
	ds_read2_b32 v[238:239], v214 offset1:1
	ds_read2_b32 v[240:241], v214 offset0:2 offset1:3
	ds_read2_b32 v[242:243], v214 offset0:4 offset1:5
	ds_read2_b32 v[244:245], v214 offset0:6 offset1:7
	s_cselect_b64 s[18:19], -1, 0
	s_and_b64 s[6:7], s[6:7], s[18:19]
	s_cmp_le_i32 s24, s34
	s_cselect_b64 s[18:19], -1, 0
	s_cmp_gt_i32 s24, 31
	s_waitcnt lgkmcnt(11)
	v_mfma_f32_16x16x32_bf16 v[8:11], v[0:3], v[66:69], 0
	s_cselect_b64 s[22:23], -1, 0
	s_and_b64 s[18:19], s[18:19], s[22:23]
	s_or_b32 s22, s24, 15
	s_waitcnt lgkmcnt(9)
	v_mfma_f32_16x16x32_bf16 v[16:19], v[12:15], v[66:69], 0
	s_cmp_lt_i32 s22, s47
	s_cselect_b64 s[22:23], -1, 0
	s_and_b64 s[6:7], s[6:7], s[18:19]
	v_mfma_f32_16x16x32_bf16 v[24:27], v[12:15], v[78:81], 0
	s_and_b64 s[24:25], s[6:7], s[22:23]
	s_cmp_eq_u32 s42, 0
	s_cselect_b64 s[22:23], -1, 0
	v_mfma_f32_16x16x32_bf16 v[138:141], v[12:15], v[114:117], 0
	s_mov_b64 s[6:7], -1
	v_mfma_f32_16x16x32_bf16 v[142:145], v[12:15], v[122:125], 0
	v_mfma_f32_16x16x32_bf16 v[12:15], v[4:7], v[70:73], v[8:11]
	s_waitcnt lgkmcnt(8)
	v_mfma_f32_16x16x32_bf16 v[8:11], v[134:137], v[70:73], v[16:19]
	v_mfma_f32_16x16x32_bf16 v[20:23], v[0:3], v[78:81], 0
	v_mfma_f32_16x16x32_bf16 v[28:31], v[0:3], v[114:117], 0
	v_mfma_f32_16x16x32_bf16 v[0:3], v[0:3], v[122:125], 0
	v_mfma_f32_16x16x32_bf16 v[16:19], v[134:137], v[94:97], v[24:27]
	v_mfma_f32_16x16x32_bf16 v[24:27], v[134:137], v[118:121], v[138:141]
	v_mfma_f32_16x16x32_bf16 v[138:141], v[4:7], v[126:129], v[0:3]
	v_mfma_f32_16x16x32_bf16 v[20:23], v[4:7], v[94:97], v[20:23]
	v_mfma_f32_16x16x32_bf16 v[28:31], v[4:7], v[118:121], v[28:31]
	v_mfma_f32_16x16x32_bf16 v[134:137], v[134:137], v[126:129], v[142:145]
	s_and_b64 vcc, exec, s[24:25]
	s_cbranch_vccnz .Lattn_fast
	s_and_b64 vcc, exec, s[22:23]
	s_cbranch_vccz .Lattn_fastm
	s_waitcnt lgkmcnt(0)
	s_and_b64 vcc, s[22:23], s[4:5]
	v_add_u32_e32 v248, 0x80, v237
	v_cmp_gt_u32_e64 s[18:19], s78, v248
	v_add_u32_e32 v248, v237, v228
	v_cmp_gt_u32_e64 s[52:53], s35, v248
	s_and_b64 s[18:19], s[18:19], s[52:53]
	s_or_b64 s[18:19], vcc, s[18:19]
	v_cndmask_b32_e32 v247, v237, v229, vcc
	v_med3_i32 v238, v247, s55, v213
	v_add_u32_e32 v247, 1, v237
	v_add_u32_e32 v248, 0x81, v237
	v_cmp_gt_u32_e64 s[22:23], s78, v248
	v_add_u32_e32 v248, v247, v228
	v_cmp_gt_u32_e64 s[52:53], s35, v248
	s_and_b64 s[22:23], s[22:23], s[52:53]
	s_or_b64 s[22:23], vcc, s[22:23]
	v_cndmask_b32_e32 v247, v247, v230, vcc
	v_med3_i32 v239, v247, s55, v213
	v_add_u32_e32 v247, 2, v237
	v_add_u32_e32 v248, 0x82, v237
	v_cmp_gt_u32_e64 s[26:27], s78, v248
	v_add_u32_e32 v248, v247, v228
	v_cmp_gt_u32_e64 s[52:53], s35, v248
	s_and_b64 s[26:27], s[26:27], s[52:53]
	s_or_b64 s[26:27], vcc, s[26:27]
	v_cndmask_b32_e32 v247, v247, v231, vcc
	v_med3_i32 v240, v247, s55, v213
	v_add_u32_e32 v247, 3, v237
	v_add_u32_e32 v248, 0x83, v237
	v_cmp_gt_u32_e64 s[30:31], s78, v248
	v_add_u32_e32 v248, v247, v228
	v_cmp_gt_u32_e64 s[52:53], s35, v248
	s_and_b64 s[30:31], s[30:31], s[52:53]
	s_or_b64 s[30:31], vcc, s[30:31]
	v_cndmask_b32_e32 v247, v247, v232, vcc
	v_med3_i32 v241, v247, s55, v213
	v_add_u32_e32 v247, 4, v237
	v_add_u32_e32 v248, 0x84, v237
	v_cmp_gt_u32_e64 s[36:37], s78, v248
	v_add_u32_e32 v248, v247, v228
	v_cmp_gt_u32_e64 s[52:53], s35, v248
	s_and_b64 s[36:37], s[36:37], s[52:53]
	s_or_b64 s[36:37], vcc, s[36:37]
	v_cndmask_b32_e32 v247, v247, v233, vcc
	v_med3_i32 v242, v247, s55, v213
	v_add_u32_e32 v247, 5, v237
	v_add_u32_e32 v248, 0x85, v237
	v_cmp_gt_u32_e64 s[40:41], s78, v248
	v_add_u32_e32 v248, v247, v228
	v_cmp_gt_u32_e64 s[52:53], s35, v248
	s_and_b64 s[40:41], s[40:41], s[52:53]
	s_or_b64 s[40:41], vcc, s[40:41]
	v_cndmask_b32_e32 v247, v247, v234, vcc
	v_med3_i32 v243, v247, s55, v213
	v_add_u32_e32 v247, 6, v237
	v_add_u32_e32 v248, 0x86, v237
	v_cmp_gt_u32_e64 s[44:45], s78, v248
	v_add_u32_e32 v248, v247, v228
	v_cmp_gt_u32_e64 s[52:53], s35, v248
	s_and_b64 s[44:45], s[44:45], s[52:53]
	s_or_b64 s[44:45], vcc, s[44:45]
	v_cndmask_b32_e32 v247, v247, v235, vcc
	v_med3_i32 v244, v247, s55, v213
	v_add_u32_e32 v247, 7, v237
	v_add_u32_e32 v248, 0x87, v237
	v_cmp_gt_u32_e64 s[48:49], s78, v248
	v_add_u32_e32 v248, v247, v228
	v_cmp_gt_u32_e64 s[52:53], s35, v248
	s_and_b64 s[48:49], s[48:49], s[52:53]
	s_or_b64 s[48:49], vcc, s[48:49]
	v_cndmask_b32_e32 v247, v247, v236, vcc
	v_med3_i32 v245, v247, s55, v213
	v_lshl_add_u32 v0, v238, 2, s62
	v_lshl_add_u32 v1, v239, 2, s62
	v_lshl_add_u32 v2, v240, 2, s62
	v_lshl_add_u32 v3, v241, 2, s62
	v_lshl_add_u32 v4, v242, 2, s62
	v_lshl_add_u32 v5, v243, 2, s62
	v_lshl_add_u32 v6, v244, 2, s62
	v_lshl_add_u32 v7, v245, 2, s62
	ds_read_b32 v0, v0 offset:512
	ds_read_b32 v1, v1 offset:512
	ds_read_b32 v2, v2 offset:512
	ds_read_b32 v3, v3 offset:512
	ds_read_b32 v4, v4 offset:512
	ds_read_b32 v5, v5 offset:512
	ds_read_b32 v6, v6 offset:512
	ds_read_b32 v7, v7 offset:512
	s_waitcnt lgkmcnt(7)
	v_add_f32_e32 v0, v12, v0
	v_exp_f32_e32 v0, v0
	s_waitcnt lgkmcnt(6)
	v_add_f32_e32 v1, v13, v1
	v_exp_f32_e32 v1, v1
	s_waitcnt lgkmcnt(5)
	v_add_f32_e32 v2, v14, v2
	v_exp_f32_e32 v2, v2
	s_waitcnt lgkmcnt(4)
	v_add_f32_e32 v3, v15, v3
	v_exp_f32_e32 v3, v3
	s_waitcnt lgkmcnt(3)
	v_add_f32_e32 v4, v8, v4
	v_cndmask_b32_e64 v0, 0, v0, s[18:19]
	v_exp_f32_e32 v4, v4
	s_waitcnt lgkmcnt(2)
	v_add_f32_e32 v5, v9, v5
	v_add_f32_e32 v142, v130, v0
	v_cndmask_b32_e64 v1, 0, v1, s[22:23]
	v_exp_f32_e32 v5, v5
	s_waitcnt lgkmcnt(1)
	v_add_f32_e32 v6, v10, v6
	v_add_f32_e32 v142, v142, v1
	v_cndmask_b32_e64 v2, 0, v2, s[26:27]
	v_exp_f32_e32 v6, v6
	s_waitcnt lgkmcnt(0)
	v_add_f32_e32 v7, v11, v7
	v_add_f32_e32 v142, v142, v2
	v_cndmask_b32_e64 v3, 0, v3, s[30:31]
	v_exp_f32_e32 v7, v7
	v_add_f32_e32 v142, v142, v3
	v_cndmask_b32_e64 v4, 0, v4, s[36:37]
	v_add_f32_e32 v142, v142, v4
	v_cndmask_b32_e64 v5, 0, v5, s[40:41]
	v_add_f32_e32 v142, v142, v5
	v_cndmask_b32_e64 v6, 0, v6, s[44:45]
	v_add_f32_e32 v146, v142, v6
	v_mov_b64_e32 v[144:145], v[132:133]
	v_cndmask_b32_e64 v7, 0, v7, s[48:49]
	v_mov_b64_e32 v[142:143], v[130:131]
	v_add_f32_e32 v246, v146, v7
	s_mov_b64 s[6:7], 0

; __device__ __forceinline__ void attn_phase(LAS unsigned char* lds, const Args& a, int j, int bid, int G, int tid) {
;     ...
; #pragma unroll 1
;                 for (int i = 0; i < 10; ++i) {
;                     const int chunk = i == 0 ? 0 : cb + i - 1;
.Lattn_skipchunk:
	s_add_i32 s39, s39, 1
	s_cmp_eq_u32 s39, 10
	s_cbranch_scc1 .LBB0_655
	s_branch .LBB0_713
